# attention prompt loop: back-edge rotation, per-tile scalar prep moved before the loop-back barrier (on top of v24)
# baseline (speedup 1.0000x reference)
; #define LAS __attribute__((address_space(3)))
; __device__ __forceinline__ void attn_stage_issue(const Params& P, LAS unsigned char* lds, const AttnStage& st, int R0, int buf, int tid) {
;     const char* ws = (const char*)P.ws; const int w = __builtin_amdgcn_readfirstlane(tid >> 6);
; #pragma unroll
;     for (int i = 0; i < 3; ++i) __builtin_amdgcn_global_load_lds((const unsigned*)(ws + (st.kofs[i] + (unsigned)R0 * st.kstr[i])), (LAS unsigned*)(lds + L_K0 + buf * KBUF + (w * 3 + i) * 1024), 16, 0, 0);
; #pragma unroll
;     for (int i = 0; i < 2; ++i) __builtin_amdgcn_global_load_lds((const unsigned*)(ws + (st.vofs[i] + (unsigned)R0 * 2u)), (LAS unsigned*)(lds + L_V0 + buf * VBUF + (w * 2 + i) * 1024), 16, 0, 0);
; template <bool NOMAX>
; __device__ __forceinline__ void attn_block(const Params& P, LAS unsigned char* lds, int qR0, int h, int kR0, int kR1, int ntiles, int jmax, int nlast, int qvalid) {
;     ...
;     for (int j = 0; j < ntiles; ++j) {
;         const int buf = j & 1;
;         if (j + 1 < ntiles) { const int Rn = (kR1 >= 0 && j + 1 >= 16) ? kR1 : kR0 + 64 * (j + 1);
;             attn_stage_issue(P, lds, st, Rn, buf ^ 1, tid); }
.LBB0_1019:
	s_and_b32 s57, s14, 1
	s_xor_b32 s12, s57, 1
	v_readfirstlane_b32 s13, v169
	s_ashr_i32 s13, s13, 6
	s_mul_i32 s58, s12, 0x6000
	s_mul_i32 s59, s13, 0xc00
	s_add_i32 s59, s58, s59
	s_lshl_b32 s12, s12, 14
	s_lshl_b32 s13, s13, 11
	s_add_i32 s60, s12, s13
	s_add_i32 s60, s60, 0xc000
	s_branch .Lattn_top_a

; #define LAS __attribute__((address_space(3)))
; __device__ __forceinline__ f32x16 mfma32(bf16x8 a, bf16x8 b, f32x16 c) { return __builtin_amdgcn_mfma_f32_32x32x16_bf16(a, b, c, 0, 0, 0); }
; template <bool NOMAX>
; __device__ __forceinline__ void attn_block(const Params& P, LAS unsigned char* lds, int qR0, int h, int kR0, int kR1, int ntiles, int jmax, int nlast, int qvalid) {
;     ...
;     for (int j = 0; j < ntiles; ++j) {
;         const int buf = j & 1;
;         if (j + 1 < ntiles) { const int Rn = (kR1 >= 0 && j + 1 >= 16) ? kR1 : kR0 + 64 * (j + 1);
;             attn_stage_issue(P, lds, st, Rn, buf ^ 1, tid); }
;         if (j <= jmax) {
;             const LAS unsigned char* kb = lds + L_K0 + buf * KBUF + r * 384; const LAS unsigned char* vb = lds + L_V0 + buf * VBUF + r * 128;
;             const LAS unsigned char* rkb = lds + L_RKT + j * 256 + 16 * hh;
;             f32x16 sacc[2];
; #pragma unroll
;             for (int kt = 0; kt < 2; ++kt) {
; #pragma unroll
;                 for (int e = 0; e < 16; ++e) sacc[kt][e] = 0.f;
; #pragma unroll
;                 for (int s = 0; s < 12; ++s) { const bf16x8 kf = *(const LAS bf16x8*)(kb + kt * (32 * 384) + (s >> 2) * 128 + oc[s & 3]); sacc[kt] = mfma32(kf, qf[s], sacc[kt]); }
;             }
; #pragma unroll
;             for (int kt = 0; kt < 2; ++kt)
; #pragma unroll
;                 for (int gq = 0; gq < 4; ++gq) { const f32x4 rk4 = *(const LAS f32x4*)(rkb + (32 * kt + 8 * gq) * 4);
; #pragma unroll
;                     for (int i = 0; i < 4; ++i) sacc[kt][4 * gq + i] *= rk4[i]; }
;     ...
;         asm volatile("s_waitcnt vmcnt(0)" ::: "memory");
;         __syncthreads();
.Lattn_tail_a:
	s_waitcnt vmcnt(0)
	s_addk_i32 s56, 0x100
	s_add_i32 s14, s14, 1
	v_add_u32_e32 v179, 0x80, v179
	v_add_u32_e32 v180, 0x80, v180
	s_and_b32 s57, s14, 1
	s_xor_b32 s12, s57, 1
	v_readfirstlane_b32 s13, v169
	s_ashr_i32 s13, s13, 6
	s_mul_i32 s58, s12, 0x6000
	s_mul_i32 s59, s13, 0xc00
	s_add_i32 s59, s58, s59
	s_lshl_b32 s12, s12, 14
	s_lshl_b32 s13, s13, 11
	s_add_i32 s60, s12, s13
	s_add_i32 s60, s60, 0xc000
	s_cmp_eq_u32 s15, s56
	v_add_u32_e32 v181, 64, v181
	s_waitcnt vmcnt(0) lgkmcnt(0)
	s_barrier
	s_cbranch_scc1 .LBB0_1024
.Lattn_top_a:
	v_cmp_le_i32_e32 vcc, s14, v163
	s_cbranch_vccz .Lattn_inact_a
	s_mul_i32 s58, s57, 0x6000
	v_add_u32_e32 v253, s58, v177
	v_add_u32_e32 v214, v253, v168
	v_add_u32_e32 v215, v253, v167
	v_add_u32_e32 v216, v253, v166
	v_add_u32_e32 v217, v253, v165
	ds_read_b128 v[182:185], v214
	ds_read_b128 v[186:189], v215
	ds_read_b128 v[190:193], v216
	ds_read_b128 v[194:197], v217
	ds_read_b128 v[198:201], v214 offset:128
	ds_read_b128 v[202:205], v215 offset:128
	v_lshl_add_u32 v254, v181, v173, v170
	s_mov_b32 m0, s59
	s_nop 0
	global_load_lds_dwordx4 v254, s[18:19]
	v_lshl_add_u32 v254, v181, v174, v171
	s_add_i32 m0, s59, 0x400
	s_nop 0
	global_load_lds_dwordx4 v254, s[18:19]
	v_lshl_add_u32 v254, v181, v175, v172
	s_add_i32 m0, s59, 0x800
	s_nop 0
	global_load_lds_dwordx4 v254, s[18:19]
	s_waitcnt lgkmcnt(5)
	v_mfma_f32_32x32x16_bf16 v[64:79], v[182:185], v[100:103], 0
	ds_read_b128 v[206:209], v216 offset:128
	s_mov_b32 m0, s60
	s_nop 0
	global_load_lds_dwordx4 v180, s[18:19]
	v_add_u32_e32 v219, s56, v178
	s_waitcnt lgkmcnt(5)
	v_mfma_f32_32x32x16_bf16 v[64:79], v[186:189], v[104:107], v[64:79]
	ds_read_b128 v[210:213], v217 offset:128
	s_add_i32 m0, s60, 0x400
	s_nop 0
	global_load_lds_dwordx4 v179, s[18:19]
	v_add_u32_e32 v219, 0x14300, v219
	s_waitcnt lgkmcnt(5)
	v_mfma_f32_32x32x16_bf16 v[64:79], v[190:193], v[108:111], v[64:79]
	ds_read_b128 v[182:185], v214 offset:256
	v_lshl_add_u32 v218, s57, 14, v176
	s_waitcnt lgkmcnt(5)
	v_mfma_f32_32x32x16_bf16 v[64:79], v[194:197], v[112:115], v[64:79]
	ds_read_b128 v[186:189], v215 offset:256
	v_sub_u32_e32 v218, v218, v253
	s_waitcnt lgkmcnt(5)
	v_mfma_f32_32x32x16_bf16 v[64:79], v[198:201], v[116:119], v[64:79]
	ds_read_b128 v[190:193], v216 offset:256
	s_waitcnt lgkmcnt(5)
	v_mfma_f32_32x32x16_bf16 v[64:79], v[202:205], v[120:123], v[64:79]
	ds_read_b128 v[194:197], v217 offset:256
	s_waitcnt lgkmcnt(5)
	v_mfma_f32_32x32x16_bf16 v[64:79], v[206:209], v[124:127], v[64:79]
	ds_read_b128 v[198:201], v214 offset:12288
	s_waitcnt lgkmcnt(5)
	v_mfma_f32_32x32x16_bf16 v[64:79], v[210:213], v[128:131], v[64:79]
	ds_read_b128 v[202:205], v215 offset:12288
	s_waitcnt lgkmcnt(5)
	v_mfma_f32_32x32x16_bf16 v[64:79], v[182:185], v[132:135], v[64:79]
	ds_read_b128 v[206:209], v216 offset:12288
	s_waitcnt lgkmcnt(5)
	v_mfma_f32_32x32x16_bf16 v[64:79], v[186:189], v[136:139], v[64:79]
	ds_read_b128 v[210:213], v217 offset:12288
	ds_read_b128 v[232:235], v219
	s_waitcnt lgkmcnt(6)
	v_mfma_f32_32x32x16_bf16 v[64:79], v[190:193], v[140:143], v[64:79]
	ds_read_b128 v[182:185], v214 offset:12416
	ds_read_b128 v[236:239], v219 offset:32
	s_waitcnt lgkmcnt(7)
	v_mfma_f32_32x32x16_bf16 v[64:79], v[194:197], v[144:147], v[64:79]
	ds_read_b128 v[186:189], v215 offset:12416
	ds_read_b128 v[240:243], v219 offset:64
	s_waitcnt lgkmcnt(8)
	v_mfma_f32_32x32x16_bf16 v[80:95], v[198:201], v[100:103], 0
	ds_read_b128 v[190:193], v216 offset:12416
	ds_read_b128 v[244:247], v219 offset:96
	s_waitcnt lgkmcnt(9)
	v_mfma_f32_32x32x16_bf16 v[80:95], v[202:205], v[104:107], v[80:95]
	ds_read_b128 v[194:197], v217 offset:12416
	s_waitcnt lgkmcnt(9)
	v_mfma_f32_32x32x16_bf16 v[80:95], v[206:209], v[108:111], v[80:95]
	ds_read_b128 v[198:201], v214 offset:12544
	s_waitcnt lgkmcnt(9)
	v_mfma_f32_32x32x16_bf16 v[80:95], v[210:213], v[112:115], v[80:95]
	ds_read_b128 v[202:205], v215 offset:12544
	s_waitcnt lgkmcnt(9)
	v_mul_f32_e32 v64, v64, v232
	v_mul_f32_e32 v65, v65, v233
	v_mul_f32_e32 v66, v66, v234
	v_mul_f32_e32 v67, v67, v235
	v_exp_f32_e32 v64, v64
	s_waitcnt lgkmcnt(8)
	v_mfma_f32_32x32x16_bf16 v[80:95], v[182:185], v[116:119], v[80:95]
	ds_read_b128 v[206:209], v216 offset:12544
	s_waitcnt lgkmcnt(8)
	v_mul_f32_e32 v68, v68, v236
	v_exp_f32_e32 v65, v65
	v_mul_f32_e32 v69, v69, v237
	v_exp_f32_e32 v66, v66
	v_mul_f32_e32 v70, v70, v238
	s_waitcnt lgkmcnt(7)
	v_mfma_f32_32x32x16_bf16 v[80:95], v[186:189], v[120:123], v[80:95]
	ds_read_b128 v[210:213], v217 offset:12544
	v_exp_f32_e32 v67, v67
	v_mul_f32_e32 v71, v71, v239
	v_add_u32_e32 v214, v214, v218
	v_add_u32_e32 v215, v215, v218
	v_add_u32_e32 v216, v216, v218
	v_add_u32_e32 v217, v217, v218
	s_waitcnt lgkmcnt(6)
	v_mfma_f32_32x32x16_bf16 v[80:95], v[190:193], v[124:127], v[80:95]
	ds_read_b128 v[182:185], v214 offset:49152
	v_exp_f32_e32 v68, v68
	v_cvt_pk_bf16_f32 v222, v64, v65
	v_exp_f32_e32 v69, v69
	v_cvt_pk_bf16_f32 v223, v66, v67
	v_exp_f32_e32 v70, v70
	s_waitcnt lgkmcnt(5)
	v_mfma_f32_32x32x16_bf16 v[80:95], v[194:197], v[128:131], v[80:95]
	ds_read_b128 v[186:189], v214 offset:53248
	v_exp_f32_e32 v71, v71
	v_cvt_pk_bf16_f32 v224, v68, v69
	v_cvt_pk_bf16_f32 v225, v70, v71
	v_mul_f32_e32 v72, v72, v240
	v_mul_f32_e32 v73, v73, v241
	s_waitcnt lgkmcnt(5)
; #define LAS __attribute__((address_space(3)))
; __device__ __forceinline__ f32x16 mfma32(bf16x8 a, bf16x8 b, f32x16 c) { return __builtin_amdgcn_mfma_f32_32x32x16_bf16(a, b, c, 0, 0, 0); }
; template <bool NOMAX>
; __device__ __forceinline__ void attn_block(const Params& P, LAS unsigned char* lds, int qR0, int h, int kR0, int kR1, int ntiles, int jmax, int nlast, int qvalid) {
;     ...
;             float ps = 0.f;
; #pragma unroll
;             for (int kt = 0; kt < 2; ++kt)
; #pragma unroll
;                 for (int e = 0; e < 16; ++e) { const float p = __builtin_amdgcn_exp2f(NOMAX ? sacc[kt][e] : sacc[kt][e] - mnew); sacc[kt][e] = p; ps += p; }
;             lrun += ps;
;             bf16x8 pf[2][2];
; #pragma unroll
;             for (int kt = 0; kt < 2; ++kt)
; #pragma unroll
;                 for (int s2 = 0; s2 < 2; ++s2) { u32x4 v; v.x = pk2(sacc[kt][8 * s2 + 0], sacc[kt][8 * s2 + 1]); v.y = pk2(sacc[kt][8 * s2 + 2], sacc[kt][8 * s2 + 3]); v.z = pk2(sacc[kt][8 * s2 + 4], sacc[kt][8 * s2 + 5]); v.w = pk2(sacc[kt][8 * s2 + 6], sacc[kt][8 * s2 + 7]); pf[kt][s2] = *(const bf16x8*)&v; }
; #pragma unroll
;             for (int dt = 0; dt < 4; ++dt)
; #pragma unroll
;                 for (int kt = 0; kt < 2; ++kt)
; #pragma unroll
;                     for (int s2 = 0; s2 < 2; ++s2) { const bf16x8 vf = *(const LAS bf16x8*)(vb + dt * (32 * 128) + oc[2 * kt + s2]);
;                         oacc[dt] = mfma32(vf, pf[kt][s2], oacc[dt]); }
	v_mfma_f32_32x32x16_bf16 v[80:95], v[198:201], v[132:135], v[80:95]
	ds_read_b128 v[190:193], v214 offset:57344
	v_mul_f32_e32 v74, v74, v242
	v_mul_f32_e32 v75, v75, v243
	v_exp_f32_e32 v72, v72
	v_mul_f32_e32 v76, v76, v244
	v_exp_f32_e32 v73, v73
	s_waitcnt lgkmcnt(5)
	v_mfma_f32_32x32x16_bf16 v[80:95], v[202:205], v[136:139], v[80:95]
	ds_read_b128 v[194:197], v214 offset:61440
	v_mul_f32_e32 v77, v77, v245
	v_exp_f32_e32 v74, v74
	v_mul_f32_e32 v78, v78, v246
	v_exp_f32_e32 v75, v75
	v_mul_f32_e32 v79, v79, v247
	s_waitcnt lgkmcnt(5)
	v_mfma_f32_32x32x16_bf16 v[80:95], v[206:209], v[140:143], v[80:95]
	ds_read_b128 v[198:201], v215 offset:49152
	v_exp_f32_e32 v76, v76
	v_cvt_pk_bf16_f32 v226, v72, v73
	v_exp_f32_e32 v77, v77
	v_cvt_pk_bf16_f32 v227, v74, v75
	ds_read_b128 v[232:235], v219 offset:128
	ds_read_b128 v[236:239], v219 offset:160
	s_waitcnt lgkmcnt(7)
	v_mfma_f32_32x32x16_bf16 v[80:95], v[210:213], v[144:147], v[80:95]
	ds_read_b128 v[202:205], v215 offset:53248
	v_exp_f32_e32 v78, v78
	v_exp_f32_e32 v79, v79
	v_cvt_pk_bf16_f32 v228, v76, v77
	v_cvt_pk_bf16_f32 v229, v78, v79
	ds_read_b128 v[240:243], v219 offset:192
	ds_read_b128 v[244:247], v219 offset:224
	s_waitcnt lgkmcnt(9)
	v_mfma_f32_32x32x16_bf16 v[48:63], v[182:185], v[222:225], v[48:63]
	ds_read_b128 v[206:209], v215 offset:57344
	v_add_f32_e32 v231, v64, v65
	v_add_f32_e32 v231, v66, v231
	v_add_f32_e32 v231, v67, v231
	v_add_f32_e32 v231, v68, v231
	s_waitcnt lgkmcnt(9)
	v_mfma_f32_32x32x16_bf16 v[32:47], v[186:189], v[222:225], v[32:47]
	ds_read_b128 v[210:213], v215 offset:61440
	v_add_f32_e32 v231, v69, v231
	v_add_f32_e32 v231, v70, v231
	v_add_f32_e32 v231, v71, v231
	v_add_f32_e32 v231, v72, v231
	s_waitcnt lgkmcnt(9)
	v_mfma_f32_32x32x16_bf16 v[16:31], v[190:193], v[222:225], v[16:31]
	ds_read_b128 v[182:185], v216 offset:49152
	v_add_f32_e32 v231, v73, v231
	v_add_f32_e32 v231, v74, v231
	v_add_f32_e32 v231, v75, v231
	v_add_f32_e32 v231, v76, v231
	s_waitcnt lgkmcnt(9)
	v_mfma_f32_32x32x16_bf16 v[0:15], v[194:197], v[222:225], v[0:15]
	ds_read_b128 v[186:189], v216 offset:53248
	s_waitcnt lgkmcnt(8)
	v_mul_f32_e32 v80, v80, v232
	v_mul_f32_e32 v81, v81, v233
	v_mul_f32_e32 v82, v82, v234
	v_mul_f32_e32 v83, v83, v235
	v_mfma_f32_32x32x16_bf16 v[48:63], v[198:201], v[226:229], v[48:63]
	ds_read_b128 v[190:193], v216 offset:57344
	v_exp_f32_e32 v80, v80
	s_waitcnt lgkmcnt(8)
	v_mul_f32_e32 v84, v84, v236
	v_exp_f32_e32 v81, v81
	v_mul_f32_e32 v85, v85, v237
	s_waitcnt lgkmcnt(7)
	v_mfma_f32_32x32x16_bf16 v[32:47], v[202:205], v[226:229], v[32:47]
	ds_read_b128 v[194:197], v216 offset:61440
	v_exp_f32_e32 v82, v82
	v_mul_f32_e32 v86, v86, v238
	v_exp_f32_e32 v83, v83
	v_mul_f32_e32 v87, v87, v239
	s_waitcnt lgkmcnt(5)
	v_mfma_f32_32x32x16_bf16 v[16:31], v[206:209], v[226:229], v[16:31]
	ds_read_b128 v[198:201], v217 offset:49152
	v_exp_f32_e32 v84, v84
	v_cvt_pk_bf16_f32 v248, v80, v81
	v_exp_f32_e32 v85, v85
	v_cvt_pk_bf16_f32 v249, v82, v83
	s_waitcnt lgkmcnt(5)
	v_mfma_f32_32x32x16_bf16 v[0:15], v[210:213], v[226:229], v[0:15]
	ds_read_b128 v[202:205], v217 offset:53248
	v_exp_f32_e32 v86, v86
	v_exp_f32_e32 v87, v87
	v_cvt_pk_bf16_f32 v250, v84, v85
	v_cvt_pk_bf16_f32 v251, v86, v87
	v_add_f32_e32 v231, v77, v231
	v_add_f32_e32 v231, v78, v231
	v_add_f32_e32 v231, v79, v231
	s_waitcnt lgkmcnt(5)
	v_mfma_f32_32x32x16_bf16 v[48:63], v[182:185], v[248:251], v[48:63]
	ds_read_b128 v[206:209], v217 offset:57344
	v_mul_f32_e32 v88, v88, v240
	v_mul_f32_e32 v89, v89, v241
	v_mul_f32_e32 v90, v90, v242
	v_mul_f32_e32 v91, v91, v243
	v_exp_f32_e32 v88, v88
	s_waitcnt lgkmcnt(5)
	v_mfma_f32_32x32x16_bf16 v[32:47], v[186:189], v[248:251], v[32:47]
	ds_read_b128 v[210:213], v217 offset:61440
	v_mul_f32_e32 v92, v92, v244
	v_exp_f32_e32 v89, v89
	v_mul_f32_e32 v93, v93, v245
	v_exp_f32_e32 v90, v90
	v_mul_f32_e32 v94, v94, v246
	s_waitcnt lgkmcnt(5)
	v_mfma_f32_32x32x16_bf16 v[16:31], v[190:193], v[248:251], v[16:31]
	v_exp_f32_e32 v91, v91
	v_mul_f32_e32 v95, v95, v247
	v_exp_f32_e32 v92, v92
	v_cvt_pk_bf16_f32 v64, v88, v89
	v_exp_f32_e32 v93, v93
	s_waitcnt lgkmcnt(4)
	v_mfma_f32_32x32x16_bf16 v[0:15], v[194:197], v[248:251], v[0:15]
	v_cvt_pk_bf16_f32 v65, v90, v91
	v_exp_f32_e32 v94, v94
	v_exp_f32_e32 v95, v95
	v_cvt_pk_bf16_f32 v66, v92, v93
	v_cvt_pk_bf16_f32 v67, v94, v95
	v_add_f32_e32 v252, v80, v81
	v_add_f32_e32 v252, v82, v252
	s_waitcnt lgkmcnt(3)
	v_mfma_f32_32x32x16_bf16 v[48:63], v[198:201], v[64:67], v[48:63]
	v_add_f32_e32 v252, v83, v252
	v_add_f32_e32 v252, v84, v252
	v_add_f32_e32 v252, v85, v252
	v_add_f32_e32 v252, v86, v252
	s_waitcnt lgkmcnt(2)
	v_mfma_f32_32x32x16_bf16 v[32:47], v[202:205], v[64:67], v[32:47]
	v_add_f32_e32 v252, v87, v252
	v_add_f32_e32 v252, v88, v252
	v_add_f32_e32 v252, v89, v252
	v_add_f32_e32 v252, v90, v252
	s_waitcnt lgkmcnt(1)
	v_mfma_f32_32x32x16_bf16 v[16:31], v[206:209], v[64:67], v[16:31]
	v_add_f32_e32 v252, v91, v252
	v_add_f32_e32 v252, v92, v252
	v_add_f32_e32 v252, v93, v252
	v_add_f32_e32 v252, v94, v252
	s_waitcnt lgkmcnt(0)
	v_mfma_f32_32x32x16_bf16 v[0:15], v[210:213], v[64:67], v[0:15]
	v_add_f32_e32 v252, v95, v252
	v_add_f32_e32 v231, v231, v252
	v_add_f32_e32 v164, v164, v231
	s_branch .Lattn_tail_a
